# neighbourhood loops: grid-row key tiles branch past the dead 31-register running-max broadcast (only context tiles need it)
# baseline (speedup 1.0000x reference)
.Lnarow_0:
	s_add_i32 s0, s26, s38
	s_add_i32 s0, s0, 2
	v_mov_b32_e32 v102, v198
	v_mov_b32_e32 v103, v181
	v_mov_b32_e32 v97, 0xff800000
	s_cmp_gt_u32 s0, 7
	v_mov_b32_e32 v96, 0xff800000
	v_mov_b32_e32 v95, 0xff800000
	v_mov_b32_e32 v94, 0xff800000
	v_mov_b32_e32 v93, 0xff800000
	v_mov_b32_e32 v92, 0xff800000
	v_mov_b32_e32 v91, 0xff800000
	v_mov_b32_e32 v90, 0xff800000
	v_mov_b32_e32 v89, 0xff800000
	v_mov_b32_e32 v88, 0xff800000
	v_mov_b32_e32 v87, 0xff800000
	v_mov_b32_e32 v86, 0xff800000
	v_mov_b32_e32 v85, 0xff800000
	v_mov_b32_e32 v84, 0xff800000
	v_mov_b32_e32 v83, 0xff800000
	v_mov_b32_e32 v82, 0xff800000
	v_mov_b32_e32 v81, 0xff800000
	v_mov_b32_e32 v80, 0xff800000
	v_mov_b32_e32 v79, 0xff800000
	v_mov_b32_e32 v78, 0xff800000
	v_mov_b32_e32 v77, 0xff800000
	v_mov_b32_e32 v76, 0xff800000
	v_mov_b32_e32 v75, 0xff800000
	v_mov_b32_e32 v74, 0xff800000
	v_mov_b32_e32 v73, 0xff800000
	v_mov_b32_e32 v72, 0xff800000
	v_mov_b32_e32 v71, 0xff800000
	v_mov_b32_e32 v70, 0xff800000
	v_mov_b32_e32 v69, 0xff800000
	v_mov_b32_e32 v68, 0xff800000
	v_mov_b32_e32 v67, 0xff800000
	v_mov_b32_e32 v66, 0xff800000
	s_cbranch_scc1 .LBB0_606
	v_med3_i32 v66, v102, 8, 56
	v_add_u32_e32 v123, -8, v66
	v_lshlrev_b32_e32 v67, 2, v103
	v_readfirstlane_b32 s0, v102
	v_sub_u32_e32 v82, v67, v66
	v_sub_u32_e32 v68, v67, v102
	v_or_b32_e32 v166, 1, v67
	v_or_b32_e32 v164, 2, v67
	v_or_b32_e32 v162, 3, v67
	v_sub_u32_e32 v115, v67, v123
	s_cmp_lt_i32 s0, 32
	s_mov_b64 s[0:1], -1
	v_add_u32_e32 v167, 40, v82
	v_add_u32_e32 v102, s11, v68
	v_sub_u32_e32 v165, v166, v66
	v_sub_u32_e32 v163, v164, v66
	v_sub_u32_e32 v122, v162, v66
	v_add_u32_e32 v114, 24, v115
	v_add_u32_e32 v111, 25, v115
	v_add_u32_e32 v110, 26, v115
	v_add_u32_e32 v103, 27, v115
	s_cbranch_scc1 .LBB0_604
	v_cmp_gt_u32_e32 vcc, 16, v167
	v_subrev_u32_e32 v66, 58, v102
	s_add_i32 s0, 0, 0x16000
	v_cndmask_b32_e32 v66, 0, v66, vcc
	v_lshl_add_u32 v66, v66, 2, s0
	ds_read_b32 v66, v66
	v_add_u32_e32 v67, 40, v165
	v_add_u32_e32 v68, 40, v163
	v_add_u32_e32 v69, 40, v122
	v_and_b32_e32 v78, -16, v82
	s_waitcnt lgkmcnt(0)
	v_sub_f32_e32 v66, v66, v196
	v_cndmask_b32_e32 v66, v219, v66, vcc
	v_cmp_gt_u32_e32 vcc, 16, v67
	v_subrev_u32_e32 v67, 57, v102
	v_subrev_u32_e32 v70, 50, v102
	v_cndmask_b32_e32 v67, 0, v67, vcc
	v_lshl_add_u32 v67, v67, 2, s0
	ds_read_b32 v67, v67
	v_add_u32_e32 v71, 49, v82
	v_add_u32_e32 v72, 50, v82
	v_add_u32_e32 v73, 51, v82
	v_add_u32_e32 v74, 56, v82
	s_waitcnt lgkmcnt(0)
	v_sub_f32_e32 v67, v67, v196
	v_cndmask_b32_e32 v67, v219, v67, vcc
	v_cmp_gt_u32_e32 vcc, 16, v68
	v_subrev_u32_e32 v68, 56, v102
	v_add_u32_e32 v75, 57, v82
	v_cndmask_b32_e32 v68, 0, v68, vcc
	v_lshl_add_u32 v68, v68, 2, s0
	ds_read_b32 v68, v68
	v_add_u32_e32 v76, 58, v82
	v_add_u32_e32 v77, 59, v82
	v_add_u32_e32 v79, 0xffffffbe, v102
	v_subrev_u32_e32 v80, 64, v102
	s_waitcnt lgkmcnt(0)
	v_sub_f32_e32 v68, v68, v196
	v_cndmask_b32_e32 v68, v219, v68, vcc
	v_cmp_gt_u32_e32 vcc, 16, v69
	v_subrev_u32_e32 v69, 55, v102
	v_subrev_u32_e32 v81, 63, v102
	v_cndmask_b32_e32 v69, 0, v69, vcc
	v_lshl_add_u32 v69, v69, 2, s0
	ds_read_b32 v69, v69
	s_waitcnt lgkmcnt(0)
	v_sub_f32_e32 v69, v69, v196
	v_cndmask_b32_e32 v69, v219, v69, vcc
	v_cmp_eq_u32_e32 vcc, s46, v78
	s_nop 1
	v_cndmask_b32_e32 v70, 0, v70, vcc
	v_lshl_add_u32 v70, v70, 2, s0
	ds_read_b32 v70, v70
	s_waitcnt lgkmcnt(0)
	v_sub_f32_e32 v70, v70, v196
	v_cndmask_b32_e32 v70, v219, v70, vcc
	v_cmp_gt_u32_e32 vcc, 16, v71
	v_subrev_u32_e32 v71, 49, v102
	s_nop 0
	v_cndmask_b32_e32 v71, 0, v71, vcc
	v_lshl_add_u32 v71, v71, 2, s0
	ds_read_b32 v71, v71
	s_waitcnt lgkmcnt(0)
	v_sub_f32_e32 v71, v71, v196
	v_cndmask_b32_e32 v71, v219, v71, vcc
	v_cmp_gt_u32_e32 vcc, 16, v72
	v_subrev_u32_e32 v72, 48, v102
	s_nop 0
	v_cndmask_b32_e32 v72, 0, v72, vcc
	v_lshl_add_u32 v72, v72, 2, s0
	ds_read_b32 v72, v72
	s_waitcnt lgkmcnt(0)
	v_sub_f32_e32 v72, v72, v196
	v_cndmask_b32_e32 v72, v219, v72, vcc
	v_cmp_gt_u32_e32 vcc, 16, v73
	v_subrev_u32_e32 v73, 47, v102
	s_nop 0
	v_cndmask_b32_e32 v73, 0, v73, vcc
	v_lshl_add_u32 v73, v73, 2, s0
	ds_read_b32 v73, v73
	s_waitcnt lgkmcnt(0)
	v_sub_f32_e32 v73, v73, v196
	v_cndmask_b32_e32 v73, v219, v73, vcc
	v_cmp_gt_u32_e32 vcc, 16, v74
	v_subrev_u32_e32 v74, 42, v102
	s_nop 0
	v_cndmask_b32_e32 v74, 0, v74, vcc
	v_lshl_add_u32 v74, v74, 2, s0
	ds_read_b32 v74, v74
	s_waitcnt lgkmcnt(0)
	v_sub_f32_e32 v74, v74, v196
	v_cndmask_b32_e32 v74, v219, v74, vcc
	v_cmp_gt_u32_e32 vcc, 16, v75
	v_subrev_u32_e32 v75, 41, v102
	s_nop 0
	v_cndmask_b32_e32 v75, 0, v75, vcc
	v_lshl_add_u32 v75, v75, 2, s0
	ds_read_b32 v75, v75
	s_waitcnt lgkmcnt(0)
	v_sub_f32_e32 v75, v75, v196
	v_cndmask_b32_e32 v75, v219, v75, vcc
	v_cmp_gt_u32_e32 vcc, 16, v76
	v_subrev_u32_e32 v76, 40, v102
	s_nop 0
	v_cndmask_b32_e32 v76, 0, v76, vcc
	v_lshl_add_u32 v76, v76, 2, s0
	ds_read_b32 v76, v76
	s_waitcnt lgkmcnt(0)
	v_sub_f32_e32 v76, v76, v196
	v_cndmask_b32_e32 v76, v219, v76, vcc
	v_cmp_gt_u32_e32 vcc, 16, v77
	v_subrev_u32_e32 v77, 39, v102
	s_nop 0
	v_cndmask_b32_e32 v77, 0, v77, vcc
	v_lshl_add_u32 v77, v77, 2, s0
	ds_read_b32 v77, v77
	s_waitcnt lgkmcnt(0)
	v_sub_f32_e32 v77, v77, v196
	v_cndmask_b32_e32 v77, v219, v77, vcc
	v_cmp_gt_u32_e32 vcc, 16, v114
	s_nop 1
	v_cndmask_b32_e32 v79, 0, v79, vcc
	v_lshl_add_u32 v79, v79, 2, s0
	ds_read_b32 v79, v79
	s_waitcnt lgkmcnt(0)
	v_sub_f32_e32 v79, v79, v196
	v_cndmask_b32_e32 v94, v219, v79, vcc
	v_cmp_eq_u32_e32 vcc, s50, v78
	v_subrev_u32_e32 v78, 34, v102
	v_add_u32_e32 v79, 0xffffffbf, v102
	v_cndmask_b32_e32 v78, 0, v78, vcc
	v_lshl_add_u32 v78, v78, 2, s0
	ds_read_b32 v78, v78
	s_waitcnt lgkmcnt(0)
	v_sub_f32_e32 v78, v78, v196
	v_cndmask_b32_e32 v78, v219, v78, vcc
	v_cmp_gt_u32_e32 vcc, 16, v111
	s_nop 1
	v_cndmask_b32_e32 v79, 0, v79, vcc
	v_lshl_add_u32 v79, v79, 2, s0
	ds_read_b32 v79, v79
	s_waitcnt lgkmcnt(0)
	v_sub_f32_e32 v79, v79, v196
	v_cndmask_b32_e32 v95, v219, v79, vcc
	v_add_u32_e32 v79, 0x41, v82
	v_cmp_gt_u32_e32 vcc, 16, v79
	v_subrev_u32_e32 v79, 33, v102
	s_nop 0
	v_cndmask_b32_e32 v79, 0, v79, vcc
	v_lshl_add_u32 v79, v79, 2, s0
	ds_read_b32 v79, v79
	s_waitcnt lgkmcnt(0)
	v_sub_f32_e32 v79, v79, v196
	v_cndmask_b32_e32 v79, v219, v79, vcc
	v_cmp_gt_u32_e32 vcc, 16, v110
	s_nop 1
	v_cndmask_b32_e32 v80, 0, v80, vcc
	v_lshl_add_u32 v80, v80, 2, s0
	ds_read_b32 v80, v80
	s_waitcnt lgkmcnt(0)
	v_sub_f32_e32 v80, v80, v196
	v_cndmask_b32_e32 v96, v219, v80, vcc
	v_add_u32_e32 v80, 0x42, v82
	v_cmp_gt_u32_e32 vcc, 16, v80
	v_subrev_u32_e32 v80, 32, v102
	s_nop 0
	v_cndmask_b32_e32 v80, 0, v80, vcc
	v_lshl_add_u32 v80, v80, 2, s0
	ds_read_b32 v80, v80
	s_waitcnt lgkmcnt(0)
	v_sub_f32_e32 v80, v80, v196
	v_cndmask_b32_e32 v80, v219, v80, vcc
	v_cmp_gt_u32_e32 vcc, 16, v103
	s_nop 1
	v_cndmask_b32_e32 v81, 0, v81, vcc
	v_lshl_add_u32 v81, v81, 2, s0
	ds_read_b32 v81, v81
	s_waitcnt lgkmcnt(0)
	v_sub_f32_e32 v81, v81, v196
	v_cndmask_b32_e32 v97, v219, v81, vcc
	v_add_u32_e32 v81, 0x43, v82
	v_cmp_gt_u32_e32 vcc, 16, v81
	v_subrev_u32_e32 v81, 31, v102
	s_nop 0
	v_cndmask_b32_e32 v81, 0, v81, vcc
	v_lshl_add_u32 v81, v81, 2, s0
	ds_read_b32 v81, v81
	s_mov_b64 s[0:1], 0
	s_waitcnt lgkmcnt(0)
	v_sub_f32_e32 v81, v81, v196
	v_cndmask_b32_e32 v81, v219, v81, vcc

.Lnarow_1:
	s_add_i32 s0, s26, s38
	s_add_i32 s0, s0, 3
	v_mov_b32_e32 v103, v181
	v_mov_b32_e32 v102, v198
	v_mov_b32_e32 v49, 0xff800000
	s_cmp_gt_u32 s0, 7
	v_mov_b32_e32 v48, 0xff800000
	v_mov_b32_e32 v47, 0xff800000
	v_mov_b32_e32 v46, 0xff800000
	v_mov_b32_e32 v45, 0xff800000
	v_mov_b32_e32 v44, 0xff800000
	v_mov_b32_e32 v43, 0xff800000
	v_mov_b32_e32 v42, 0xff800000
	v_mov_b32_e32 v41, 0xff800000
	v_mov_b32_e32 v40, 0xff800000
	v_mov_b32_e32 v39, 0xff800000
	v_mov_b32_e32 v38, 0xff800000
	v_mov_b32_e32 v37, 0xff800000
	v_mov_b32_e32 v36, 0xff800000
	v_mov_b32_e32 v35, 0xff800000
	v_mov_b32_e32 v34, 0xff800000
	v_mov_b32_e32 v65, 0xff800000
	v_mov_b32_e32 v64, 0xff800000
	v_mov_b32_e32 v63, 0xff800000
	v_mov_b32_e32 v62, 0xff800000
	v_mov_b32_e32 v61, 0xff800000
	v_mov_b32_e32 v60, 0xff800000
	v_mov_b32_e32 v59, 0xff800000
	v_mov_b32_e32 v58, 0xff800000
	v_mov_b32_e32 v57, 0xff800000
	v_mov_b32_e32 v56, 0xff800000
	v_mov_b32_e32 v55, 0xff800000
	v_mov_b32_e32 v54, 0xff800000
	v_mov_b32_e32 v53, 0xff800000
	v_mov_b32_e32 v52, 0xff800000
	v_mov_b32_e32 v51, 0xff800000
	v_mov_b32_e32 v50, 0xff800000
	s_cbranch_scc1 .LBB0_617
	v_med3_i32 v34, v102, 8, 56
	v_add_u32_e32 v123, -8, v34
	v_lshlrev_b32_e32 v35, 2, v103
	v_readfirstlane_b32 s0, v102
	v_sub_u32_e32 v50, v35, v34
	v_sub_u32_e32 v36, v35, v102
	v_or_b32_e32 v167, 1, v35
	v_or_b32_e32 v164, 2, v35
	v_or_b32_e32 v162, 3, v35
	v_sub_u32_e32 v115, v35, v123
	s_cmp_lt_i32 s0, 32
	s_mov_b64 s[0:1], -1
	v_add_u32_e32 v168, 40, v50
	v_add_u32_e32 v102, s11, v36
	v_sub_u32_e32 v165, v167, v34
	v_sub_u32_e32 v163, v164, v34
	v_sub_u32_e32 v122, v162, v34
	v_add_u32_e32 v114, 24, v115
	v_add_u32_e32 v111, 25, v115
	v_add_u32_e32 v110, 26, v115
	v_add_u32_e32 v103, 27, v115
	s_cbranch_scc1 .LBB0_615
	v_cmp_gt_u32_e32 vcc, 16, v168
	v_subrev_u32_e32 v34, 27, v102
	s_add_i32 s0, 0, 0x16000
	v_cndmask_b32_e32 v34, 0, v34, vcc
	v_lshl_add_u32 v34, v34, 2, s0
	ds_read_b32 v34, v34
	v_add_u32_e32 v35, 40, v165
	v_add_u32_e32 v36, 40, v163
	v_add_u32_e32 v37, 40, v122
	v_and_b32_e32 v46, -16, v50
	s_waitcnt lgkmcnt(0)
	v_sub_f32_e32 v34, v34, v196
	v_cndmask_b32_e32 v34, v219, v34, vcc
	v_cmp_gt_u32_e32 vcc, 16, v35
	v_subrev_u32_e32 v35, 26, v102
	v_subrev_u32_e32 v38, 19, v102
	v_cndmask_b32_e32 v35, 0, v35, vcc
	v_lshl_add_u32 v35, v35, 2, s0
	ds_read_b32 v35, v35
	v_add_u32_e32 v39, 49, v50
	v_add_u32_e32 v40, 50, v50
	v_add_u32_e32 v41, 51, v50
	v_add_u32_e32 v42, 56, v50
	s_waitcnt lgkmcnt(0)
	v_sub_f32_e32 v35, v35, v196
	v_cndmask_b32_e32 v35, v219, v35, vcc
	v_cmp_gt_u32_e32 vcc, 16, v36
	v_subrev_u32_e32 v36, 25, v102
	v_add_u32_e32 v43, 57, v50
	v_cndmask_b32_e32 v36, 0, v36, vcc
	v_lshl_add_u32 v36, v36, 2, s0
	ds_read_b32 v36, v36
	v_add_u32_e32 v44, 58, v50
	v_add_u32_e32 v45, 59, v50
	v_subrev_u32_e32 v47, 35, v102
	v_subrev_u32_e32 v48, 33, v102
	s_waitcnt lgkmcnt(0)
	v_sub_f32_e32 v36, v36, v196
	v_cndmask_b32_e32 v36, v219, v36, vcc
	v_cmp_gt_u32_e32 vcc, 16, v37
	v_subrev_u32_e32 v37, 24, v102
	v_subrev_u32_e32 v49, 32, v102
	v_cndmask_b32_e32 v37, 0, v37, vcc
	v_lshl_add_u32 v37, v37, 2, s0
	ds_read_b32 v37, v37
	s_waitcnt lgkmcnt(0)
	v_sub_f32_e32 v37, v37, v196
	v_cndmask_b32_e32 v37, v219, v37, vcc
	v_cmp_eq_u32_e32 vcc, s46, v46
	s_nop 1
	v_cndmask_b32_e32 v38, 0, v38, vcc
	v_lshl_add_u32 v38, v38, 2, s0
	ds_read_b32 v38, v38
	s_waitcnt lgkmcnt(0)
	v_sub_f32_e32 v38, v38, v196
	v_cndmask_b32_e32 v38, v219, v38, vcc
	v_cmp_gt_u32_e32 vcc, 16, v39
	v_subrev_u32_e32 v39, 18, v102
	s_nop 0
	v_cndmask_b32_e32 v39, 0, v39, vcc
	v_lshl_add_u32 v39, v39, 2, s0
	ds_read_b32 v39, v39
	s_waitcnt lgkmcnt(0)
	v_sub_f32_e32 v39, v39, v196
	v_cndmask_b32_e32 v39, v219, v39, vcc
	v_cmp_gt_u32_e32 vcc, 16, v40
	v_subrev_u32_e32 v40, 17, v102
	s_nop 0
	v_cndmask_b32_e32 v40, 0, v40, vcc
	v_lshl_add_u32 v40, v40, 2, s0
	ds_read_b32 v40, v40
	s_waitcnt lgkmcnt(0)
	v_sub_f32_e32 v40, v40, v196
	v_cndmask_b32_e32 v40, v219, v40, vcc
	v_cmp_gt_u32_e32 vcc, 16, v41
	v_add_u32_e32 v41, -16, v102
	s_nop 0
	v_cndmask_b32_e32 v41, 0, v41, vcc
	v_lshl_add_u32 v41, v41, 2, s0
	ds_read_b32 v41, v41
	s_waitcnt lgkmcnt(0)
	v_sub_f32_e32 v41, v41, v196
	v_cndmask_b32_e32 v41, v219, v41, vcc
	v_cmp_gt_u32_e32 vcc, 16, v42
	v_add_u32_e32 v42, -11, v102
	s_nop 0
	v_cndmask_b32_e32 v42, 0, v42, vcc
	v_lshl_add_u32 v42, v42, 2, s0
	ds_read_b32 v42, v42
	s_waitcnt lgkmcnt(0)
	v_sub_f32_e32 v42, v42, v196
	v_cndmask_b32_e32 v42, v219, v42, vcc
	v_cmp_gt_u32_e32 vcc, 16, v43
	v_add_u32_e32 v43, -10, v102
	s_nop 0
	v_cndmask_b32_e32 v43, 0, v43, vcc
	v_lshl_add_u32 v43, v43, 2, s0
	ds_read_b32 v43, v43
	s_waitcnt lgkmcnt(0)
	v_sub_f32_e32 v43, v43, v196
	v_cndmask_b32_e32 v43, v219, v43, vcc
	v_cmp_gt_u32_e32 vcc, 16, v44
	v_add_u32_e32 v44, -9, v102
	s_nop 0
	v_cndmask_b32_e32 v44, 0, v44, vcc
	v_lshl_add_u32 v44, v44, 2, s0
	ds_read_b32 v44, v44
	s_waitcnt lgkmcnt(0)
	v_sub_f32_e32 v44, v44, v196
	v_cndmask_b32_e32 v44, v219, v44, vcc
	v_cmp_gt_u32_e32 vcc, 16, v45
	v_add_u32_e32 v45, -8, v102
	s_nop 0
	v_cndmask_b32_e32 v45, 0, v45, vcc
	v_lshl_add_u32 v45, v45, 2, s0
	ds_read_b32 v45, v45
	s_waitcnt lgkmcnt(0)
	v_sub_f32_e32 v45, v45, v196
	v_cndmask_b32_e32 v45, v219, v45, vcc
	v_cmp_gt_u32_e32 vcc, 16, v114
	s_nop 1
	v_cndmask_b32_e32 v47, 0, v47, vcc
	v_lshl_add_u32 v47, v47, 2, s0
	ds_read_b32 v47, v47
	s_waitcnt lgkmcnt(0)
	v_sub_f32_e32 v47, v47, v196
	v_cndmask_b32_e32 v62, v219, v47, vcc
	v_cmp_eq_u32_e32 vcc, s50, v46
	v_add_u32_e32 v46, -3, v102
	v_subrev_u32_e32 v47, 34, v102
	v_cndmask_b32_e32 v46, 0, v46, vcc
	v_lshl_add_u32 v46, v46, 2, s0
	ds_read_b32 v46, v46
	s_waitcnt lgkmcnt(0)
	v_sub_f32_e32 v46, v46, v196
	v_cndmask_b32_e32 v46, v219, v46, vcc
	v_cmp_gt_u32_e32 vcc, 16, v111
	s_nop 1
	v_cndmask_b32_e32 v47, 0, v47, vcc
	v_lshl_add_u32 v47, v47, 2, s0
	ds_read_b32 v47, v47
	s_waitcnt lgkmcnt(0)
	v_sub_f32_e32 v47, v47, v196
	v_cndmask_b32_e32 v63, v219, v47, vcc
	v_add_u32_e32 v47, 0x41, v50
	v_cmp_gt_u32_e32 vcc, 16, v47
	v_add_u32_e32 v47, -2, v102
	s_nop 0
	v_cndmask_b32_e32 v47, 0, v47, vcc
	v_lshl_add_u32 v47, v47, 2, s0
	ds_read_b32 v47, v47
	s_waitcnt lgkmcnt(0)
	v_sub_f32_e32 v47, v47, v196
	v_cndmask_b32_e32 v47, v219, v47, vcc
	v_cmp_gt_u32_e32 vcc, 16, v110
	s_nop 1
	v_cndmask_b32_e32 v48, 0, v48, vcc
	v_lshl_add_u32 v48, v48, 2, s0
	ds_read_b32 v48, v48
	s_waitcnt lgkmcnt(0)
	v_sub_f32_e32 v48, v48, v196
	v_cndmask_b32_e32 v64, v219, v48, vcc
	v_add_u32_e32 v48, 0x42, v50
	v_cmp_gt_u32_e32 vcc, 16, v48
	v_add_u32_e32 v48, -1, v102
	s_nop 0
	v_cndmask_b32_e32 v48, 0, v48, vcc
	v_lshl_add_u32 v48, v48, 2, s0
	ds_read_b32 v48, v48
	s_waitcnt lgkmcnt(0)
	v_sub_f32_e32 v48, v48, v196
	v_cndmask_b32_e32 v48, v219, v48, vcc
	v_cmp_gt_u32_e32 vcc, 16, v103
	s_nop 1
	v_cndmask_b32_e32 v49, 0, v49, vcc
	v_lshl_add_u32 v49, v49, 2, s0
	ds_read_b32 v49, v49
	s_waitcnt lgkmcnt(0)
	v_sub_f32_e32 v49, v49, v196
	v_cndmask_b32_e32 v65, v219, v49, vcc
	v_add_u32_e32 v49, 0x43, v50
	v_cmp_gt_u32_e32 vcc, 16, v49
	s_nop 1
	v_cndmask_b32_e32 v49, 0, v102, vcc
	v_lshl_add_u32 v49, v49, 2, s0
	ds_read_b32 v49, v49
	s_mov_b64 s[0:1], 0
	s_waitcnt lgkmcnt(0)
	v_sub_f32_e32 v49, v49, v196
	v_cndmask_b32_e32 v49, v219, v49, vcc

.Lnarow_2:
	s_add_i32 s0, s26, s38
	s_add_i32 s0, s0, 2
	v_mov_b32_e32 v103, v181
	v_mov_b32_e32 v102, v198
	v_mov_b32_e32 v97, 0xff800000
	s_cmp_gt_u32 s0, 7
	v_mov_b32_e32 v96, 0xff800000
	v_mov_b32_e32 v95, 0xff800000
	v_mov_b32_e32 v94, 0xff800000
	v_mov_b32_e32 v93, 0xff800000
	v_mov_b32_e32 v92, 0xff800000
	v_mov_b32_e32 v91, 0xff800000
	v_mov_b32_e32 v90, 0xff800000
	v_mov_b32_e32 v89, 0xff800000
	v_mov_b32_e32 v88, 0xff800000
	v_mov_b32_e32 v87, 0xff800000
	v_mov_b32_e32 v86, 0xff800000
	v_mov_b32_e32 v85, 0xff800000
	v_mov_b32_e32 v84, 0xff800000
	v_mov_b32_e32 v83, 0xff800000
	v_mov_b32_e32 v82, 0xff800000
	v_mov_b32_e32 v81, 0xff800000
	v_mov_b32_e32 v80, 0xff800000
	v_mov_b32_e32 v79, 0xff800000
	v_mov_b32_e32 v78, 0xff800000
	v_mov_b32_e32 v77, 0xff800000
	v_mov_b32_e32 v76, 0xff800000
	v_mov_b32_e32 v75, 0xff800000
	v_mov_b32_e32 v74, 0xff800000
	v_mov_b32_e32 v73, 0xff800000
	v_mov_b32_e32 v72, 0xff800000
	v_mov_b32_e32 v71, 0xff800000
	v_mov_b32_e32 v70, 0xff800000
	v_mov_b32_e32 v69, 0xff800000
	v_mov_b32_e32 v68, 0xff800000
	v_mov_b32_e32 v67, 0xff800000
	v_mov_b32_e32 v66, 0xff800000
	s_cbranch_scc1 .LBB0_778
	v_med3_i32 v66, v102, 8, 56
	v_add_u32_e32 v123, -8, v66
	v_lshlrev_b32_e32 v67, 2, v103
	v_readfirstlane_b32 s0, v102
	v_sub_u32_e32 v82, v67, v66
	v_sub_u32_e32 v68, v67, v102
	v_or_b32_e32 v166, 1, v67
	v_or_b32_e32 v164, 2, v67
	v_or_b32_e32 v162, 3, v67
	v_sub_u32_e32 v115, v67, v123
	s_cmp_lt_i32 s0, 32
	s_mov_b64 s[0:1], -1
	v_add_u32_e32 v167, 40, v82
	v_add_u32_e32 v102, s11, v68
	v_sub_u32_e32 v165, v166, v66
	v_sub_u32_e32 v163, v164, v66
	v_sub_u32_e32 v122, v162, v66
	v_add_u32_e32 v114, 24, v115
	v_add_u32_e32 v111, 25, v115
	v_add_u32_e32 v110, 26, v115
	v_add_u32_e32 v103, 27, v115
	s_cbranch_scc1 .LBB0_776
	v_cmp_gt_u32_e32 vcc, 16, v167
	v_subrev_u32_e32 v66, 58, v102
	s_add_i32 s0, 0, 0x16000
	v_cndmask_b32_e32 v66, 0, v66, vcc
	v_lshl_add_u32 v66, v66, 2, s0
	ds_read_b32 v66, v66
	v_add_u32_e32 v67, 40, v165
	v_add_u32_e32 v68, 40, v163
	v_add_u32_e32 v69, 40, v122
	v_and_b32_e32 v78, -16, v82
	s_waitcnt lgkmcnt(0)
	v_sub_f32_e32 v66, v66, v196
	v_cndmask_b32_e32 v66, v219, v66, vcc
	v_cmp_gt_u32_e32 vcc, 16, v67
	v_subrev_u32_e32 v67, 57, v102
	v_subrev_u32_e32 v70, 50, v102
	v_cndmask_b32_e32 v67, 0, v67, vcc
	v_lshl_add_u32 v67, v67, 2, s0
	ds_read_b32 v67, v67
	v_add_u32_e32 v71, 49, v82
	v_add_u32_e32 v72, 50, v82
	v_add_u32_e32 v73, 51, v82
	v_add_u32_e32 v74, 56, v82
	s_waitcnt lgkmcnt(0)
	v_sub_f32_e32 v67, v67, v196
	v_cndmask_b32_e32 v67, v219, v67, vcc
	v_cmp_gt_u32_e32 vcc, 16, v68
	v_subrev_u32_e32 v68, 56, v102
	v_add_u32_e32 v75, 57, v82
	v_cndmask_b32_e32 v68, 0, v68, vcc
	v_lshl_add_u32 v68, v68, 2, s0
	ds_read_b32 v68, v68
	v_add_u32_e32 v76, 58, v82
	v_add_u32_e32 v77, 59, v82
	v_add_u32_e32 v79, 0xffffffbe, v102
	v_subrev_u32_e32 v80, 64, v102
	s_waitcnt lgkmcnt(0)
	v_sub_f32_e32 v68, v68, v196
	v_cndmask_b32_e32 v68, v219, v68, vcc
	v_cmp_gt_u32_e32 vcc, 16, v69
	v_subrev_u32_e32 v69, 55, v102
	v_subrev_u32_e32 v81, 63, v102
	v_cndmask_b32_e32 v69, 0, v69, vcc
	v_lshl_add_u32 v69, v69, 2, s0
	ds_read_b32 v69, v69
	s_waitcnt lgkmcnt(0)
	v_sub_f32_e32 v69, v69, v196
	v_cndmask_b32_e32 v69, v219, v69, vcc
	v_cmp_eq_u32_e32 vcc, s46, v78
	s_nop 1
	v_cndmask_b32_e32 v70, 0, v70, vcc
	v_lshl_add_u32 v70, v70, 2, s0
	ds_read_b32 v70, v70
	s_waitcnt lgkmcnt(0)
	v_sub_f32_e32 v70, v70, v196
	v_cndmask_b32_e32 v70, v219, v70, vcc
	v_cmp_gt_u32_e32 vcc, 16, v71
	v_subrev_u32_e32 v71, 49, v102
	s_nop 0
	v_cndmask_b32_e32 v71, 0, v71, vcc
	v_lshl_add_u32 v71, v71, 2, s0
	ds_read_b32 v71, v71
	s_waitcnt lgkmcnt(0)
	v_sub_f32_e32 v71, v71, v196
	v_cndmask_b32_e32 v71, v219, v71, vcc
	v_cmp_gt_u32_e32 vcc, 16, v72
	v_subrev_u32_e32 v72, 48, v102
	s_nop 0
	v_cndmask_b32_e32 v72, 0, v72, vcc
	v_lshl_add_u32 v72, v72, 2, s0
	ds_read_b32 v72, v72
	s_waitcnt lgkmcnt(0)
	v_sub_f32_e32 v72, v72, v196
	v_cndmask_b32_e32 v72, v219, v72, vcc
	v_cmp_gt_u32_e32 vcc, 16, v73
	v_subrev_u32_e32 v73, 47, v102
	s_nop 0
	v_cndmask_b32_e32 v73, 0, v73, vcc
	v_lshl_add_u32 v73, v73, 2, s0
	ds_read_b32 v73, v73
	s_waitcnt lgkmcnt(0)
	v_sub_f32_e32 v73, v73, v196
	v_cndmask_b32_e32 v73, v219, v73, vcc
	v_cmp_gt_u32_e32 vcc, 16, v74
	v_subrev_u32_e32 v74, 42, v102
	s_nop 0
	v_cndmask_b32_e32 v74, 0, v74, vcc
	v_lshl_add_u32 v74, v74, 2, s0
	ds_read_b32 v74, v74
	s_waitcnt lgkmcnt(0)
	v_sub_f32_e32 v74, v74, v196
	v_cndmask_b32_e32 v74, v219, v74, vcc
	v_cmp_gt_u32_e32 vcc, 16, v75
	v_subrev_u32_e32 v75, 41, v102
	s_nop 0
	v_cndmask_b32_e32 v75, 0, v75, vcc
	v_lshl_add_u32 v75, v75, 2, s0
	ds_read_b32 v75, v75
	s_waitcnt lgkmcnt(0)
	v_sub_f32_e32 v75, v75, v196
	v_cndmask_b32_e32 v75, v219, v75, vcc
	v_cmp_gt_u32_e32 vcc, 16, v76
	v_subrev_u32_e32 v76, 40, v102
	s_nop 0
	v_cndmask_b32_e32 v76, 0, v76, vcc
	v_lshl_add_u32 v76, v76, 2, s0
	ds_read_b32 v76, v76
	s_waitcnt lgkmcnt(0)
	v_sub_f32_e32 v76, v76, v196
	v_cndmask_b32_e32 v76, v219, v76, vcc
	v_cmp_gt_u32_e32 vcc, 16, v77
	v_subrev_u32_e32 v77, 39, v102
	s_nop 0
	v_cndmask_b32_e32 v77, 0, v77, vcc
	v_lshl_add_u32 v77, v77, 2, s0
	ds_read_b32 v77, v77
	s_waitcnt lgkmcnt(0)
	v_sub_f32_e32 v77, v77, v196
	v_cndmask_b32_e32 v77, v219, v77, vcc
	v_cmp_gt_u32_e32 vcc, 16, v114
	s_nop 1
	v_cndmask_b32_e32 v79, 0, v79, vcc
	v_lshl_add_u32 v79, v79, 2, s0
	ds_read_b32 v79, v79
	s_waitcnt lgkmcnt(0)
	v_sub_f32_e32 v79, v79, v196
	v_cndmask_b32_e32 v94, v219, v79, vcc
	v_cmp_eq_u32_e32 vcc, s50, v78
	v_subrev_u32_e32 v78, 34, v102
	v_add_u32_e32 v79, 0xffffffbf, v102
	v_cndmask_b32_e32 v78, 0, v78, vcc
	v_lshl_add_u32 v78, v78, 2, s0
	ds_read_b32 v78, v78
	s_waitcnt lgkmcnt(0)
	v_sub_f32_e32 v78, v78, v196
	v_cndmask_b32_e32 v78, v219, v78, vcc
	v_cmp_gt_u32_e32 vcc, 16, v111
	s_nop 1
	v_cndmask_b32_e32 v79, 0, v79, vcc
	v_lshl_add_u32 v79, v79, 2, s0
	ds_read_b32 v79, v79
	s_waitcnt lgkmcnt(0)
	v_sub_f32_e32 v79, v79, v196
	v_cndmask_b32_e32 v95, v219, v79, vcc
	v_add_u32_e32 v79, 0x41, v82
	v_cmp_gt_u32_e32 vcc, 16, v79
	v_subrev_u32_e32 v79, 33, v102
	s_nop 0
	v_cndmask_b32_e32 v79, 0, v79, vcc
	v_lshl_add_u32 v79, v79, 2, s0
	ds_read_b32 v79, v79
	s_waitcnt lgkmcnt(0)
	v_sub_f32_e32 v79, v79, v196
	v_cndmask_b32_e32 v79, v219, v79, vcc
	v_cmp_gt_u32_e32 vcc, 16, v110
	s_nop 1
	v_cndmask_b32_e32 v80, 0, v80, vcc
	v_lshl_add_u32 v80, v80, 2, s0
	ds_read_b32 v80, v80
	s_waitcnt lgkmcnt(0)
	v_sub_f32_e32 v80, v80, v196
	v_cndmask_b32_e32 v96, v219, v80, vcc
	v_add_u32_e32 v80, 0x42, v82
	v_cmp_gt_u32_e32 vcc, 16, v80
	v_subrev_u32_e32 v80, 32, v102
	s_nop 0
	v_cndmask_b32_e32 v80, 0, v80, vcc
	v_lshl_add_u32 v80, v80, 2, s0
	ds_read_b32 v80, v80
	s_waitcnt lgkmcnt(0)
	v_sub_f32_e32 v80, v80, v196
	v_cndmask_b32_e32 v80, v219, v80, vcc
	v_cmp_gt_u32_e32 vcc, 16, v103
	s_nop 1
	v_cndmask_b32_e32 v81, 0, v81, vcc
	v_lshl_add_u32 v81, v81, 2, s0
	ds_read_b32 v81, v81
	s_waitcnt lgkmcnt(0)
	v_sub_f32_e32 v81, v81, v196
	v_cndmask_b32_e32 v97, v219, v81, vcc
	v_add_u32_e32 v81, 0x43, v82
	v_cmp_gt_u32_e32 vcc, 16, v81
	v_subrev_u32_e32 v81, 31, v102
	s_nop 0
	v_cndmask_b32_e32 v81, 0, v81, vcc
	v_lshl_add_u32 v81, v81, 2, s0
	ds_read_b32 v81, v81
	s_mov_b64 s[0:1], 0
	s_waitcnt lgkmcnt(0)
	v_sub_f32_e32 v81, v81, v196
	v_cndmask_b32_e32 v81, v219, v81, vcc
